# Resid GEMM epilogues: last row-stat store pair of each tile also merged (8 -> 4 per wave per tile)
# baseline (speedup 1.0000x reference)
.LBB0_410:
	s_or_b64 exec, exec, s[36:37]
	s_nop 4
	v_permlane16_swap_b32 v236, v232
	v_permlane16_swap_b32 v237, v233
	v_permlane16_swap_b32 v238, v234
	s_mov_b64 s[36:37], exec
	s_mov_b64 exec, 0xffffffff
	global_store_dword v[236:237], v238, off
	s_mov_b64 exec, s[36:37]
	s_mov_b64 s[18:19], 0xa0
	v_lshl_add_u64 v[50:51], v[166:167], 0, s[18:19]
	s_waitcnt lgkmcnt(0)
	v_lshlrev_b64 v[32:33], 12, v[50:51]
	v_lshl_add_u64 v[32:33], v[168:169], 0, v[32:33]
	global_load_dwordx4 v[52:55], v[32:33], off
	global_load_dwordx4 v[56:59], v[32:33], off offset:64
	global_load_dwordx4 v[60:63], v[32:33], off offset:512
	global_load_dwordx4 v[64:67], v[32:33], off offset:576
	s_mov_b64 s[18:19], 0xb0
	v_lshl_add_u64 v[48:49], v[166:167], 0, s[18:19]
	v_lshlrev_b64 v[32:33], 12, v[48:49]
	v_lshl_add_u64 v[32:33], v[168:169], 0, v[32:33]
	global_load_dwordx4 v[44:47], v[32:33], off
	global_load_dwordx4 v[40:43], v[32:33], off offset:64
	global_load_dwordx4 v[36:39], v[32:33], off offset:512
	s_nop 0
	global_load_dwordx4 v[32:35], v[32:33], off offset:576
	v_lshlrev_b64 v[68:69], 10, v[50:51]
	v_lshl_add_u64 v[68:69], v[68:69], 0, v[164:165]
	s_waitcnt vmcnt(0)
	s_waitcnt vmcnt(0)
	v_pk_fma_f32 v[30:31], v[30:31], 0.5, v[54:55] op_sel_hi:[1,0,1]
	v_lshlrev_b64 v[54:55], 1, v[68:69]
	v_pk_fma_f32 v[28:29], v[28:29], 0.5, v[52:53] op_sel_hi:[1,0,1]
	v_lshl_add_u64 v[52:53], v[68:69], 2, s[78:79]
	v_lshl_add_u64 v[68:69], s[0:1], 0, v[54:55]
	global_store_dwordx4 v[52:53], v[28:31], off
	v_cvt_pk_bf16_f32 v70, v28, v29
	v_cvt_pk_bf16_f32 v71, v30, v31
	s_nop 1
	v_mov_b32_e32 v240, v70
	v_mov_b32_e32 v241, v71
	v_lshl_add_u64 v[244:245], v[68:69], 0, v[246:247]
	v_mul_f32_e32 v68, v28, v28
	v_fmac_f32_e32 v68, v29, v29
	v_pk_fma_f32 v[26:27], v[26:27], 0.5, v[58:59] op_sel_hi:[1,0,1]
	v_pk_fma_f32 v[24:25], v[24:25], 0.5, v[56:57] op_sel_hi:[1,0,1]
	v_fmac_f32_e32 v68, v30, v30
	global_store_dwordx4 v[52:53], v[24:27], off offset:64
	v_cvt_pk_bf16_f32 v30, v24, v25
	v_or_b32_e32 v28, 32, v54
	v_mov_b32_e32 v29, v55
	v_mul_f32_e32 v24, v24, v24
	v_fmac_f32_e32 v24, v25, v25
	v_fmac_f32_e32 v24, v26, v26
	v_fmac_f32_e32 v68, v31, v31
	v_lshl_add_u64 v[28:29], s[0:1], 0, v[28:29]
	v_fmac_f32_e32 v24, v27, v27
	v_pk_fma_f32 v[22:23], v[22:23], 0.5, v[62:63] op_sel_hi:[1,0,1]
	v_pk_fma_f32 v[20:21], v[20:21], 0.5, v[60:61] op_sel_hi:[1,0,1]
	v_cvt_pk_bf16_f32 v31, v26, v27
	v_mov_b32_e32 v242, v30
	v_mov_b32_e32 v243, v31
	s_nop 1
	v_permlane16_swap_b32 v240, v242
	v_permlane16_swap_b32 v241, v243
	global_store_dwordx4 v[244:245], v[240:243], off
	v_add_f32_e32 v28, v68, v24
	global_store_dwordx4 v[52:53], v[20:23], off offset:512
	v_or_b32_e32 v24, 0x100, v54
	v_mov_b32_e32 v25, v55
	v_cvt_pk_bf16_f32 v26, v20, v21
	v_mul_f32_e32 v20, v20, v20
	v_lshl_add_u64 v[24:25], s[0:1], 0, v[24:25]
	v_fmac_f32_e32 v20, v21, v21
	v_pk_fma_f32 v[18:19], v[18:19], 0.5, v[66:67] op_sel_hi:[1,0,1]
	v_pk_fma_f32 v[16:17], v[16:17], 0.5, v[64:65] op_sel_hi:[1,0,1]
	v_cvt_pk_bf16_f32 v27, v22, v23
	s_nop 1
	v_mov_b32_e32 v240, v26
	v_mov_b32_e32 v241, v27
	v_lshl_add_u64 v[244:245], v[24:25], 0, v[246:247]
	v_fmac_f32_e32 v20, v22, v22
	global_store_dwordx4 v[52:53], v[16:19], off offset:576
	v_cvt_pk_bf16_f32 v22, v16, v17
	v_fmac_f32_e32 v20, v23, v23
	v_add_f32_e32 v24, v28, v20
	v_mul_f32_e32 v16, v16, v16
	v_fmac_f32_e32 v16, v17, v17
	v_fmac_f32_e32 v16, v18, v18
	v_fmac_f32_e32 v16, v19, v19
	v_add_f32_e32 v16, v24, v16
	ds_bpermute_b32 v17, v116, v16
	v_or_b32_e32 v54, 0x120, v54
	v_lshl_add_u64 v[20:21], s[0:1], 0, v[54:55]
	v_cvt_pk_bf16_f32 v23, v18, v19
	v_mov_b32_e32 v242, v22
	v_mov_b32_e32 v243, v23
	s_nop 1
	v_permlane16_swap_b32 v240, v242
	v_permlane16_swap_b32 v241, v243
	global_store_dwordx4 v[244:245], v[240:243], off
	s_waitcnt lgkmcnt(0)
	v_add_f32_e32 v16, v16, v17
	ds_bpermute_b32 v17, v117, v16
	s_and_saveexec_b64 s[36:37], s[8:9]
	s_cbranch_execz .LBB0_412
	v_lshlrev_b64 v[18:19], 6, v[50:51]
	v_lshl_add_u64 v[18:19], s[2:3], 0, v[18:19]
	v_lshl_add_u64 v[18:19], s[16:17], 2, v[18:19]
	s_lshl_b32 s6, s83, 2
	v_lshl_add_u64 v[18:19], v[18:19], 0, s[6:7]
	s_waitcnt lgkmcnt(0)
	v_add_f32_e32 v16, v16, v17
	v_mov_b32_e32 v232, v18
	v_mov_b32_e32 v233, v19
	v_mov_b32_e32 v234, v16
.LBB0_412:
	s_or_b64 exec, exec, s[36:37]
	s_waitcnt lgkmcnt(0)
	v_lshlrev_b64 v[16:17], 10, v[48:49]
	v_lshl_add_u64 v[16:17], v[16:17], 0, v[164:165]
	v_lshl_add_u64 v[18:19], v[16:17], 2, s[78:79]
	v_lshlrev_b64 v[16:17], 1, v[16:17]
	v_pk_fma_f32 v[14:15], v[14:15], 0.5, v[46:47] op_sel_hi:[1,0,1]
	v_pk_fma_f32 v[12:13], v[12:13], 0.5, v[44:45] op_sel_hi:[1,0,1]
	v_lshl_add_u64 v[20:21], s[0:1], 0, v[16:17]
	global_store_dwordx4 v[18:19], v[12:15], off
	v_cvt_pk_bf16_f32 v22, v12, v13
	v_cvt_pk_bf16_f32 v23, v14, v15
	s_nop 1
	v_mov_b32_e32 v240, v22
	v_mov_b32_e32 v241, v23
	v_lshl_add_u64 v[244:245], v[20:21], 0, v[246:247]
	v_mul_f32_e32 v20, v12, v12
	v_fmac_f32_e32 v20, v13, v13
	v_pk_fma_f32 v[10:11], v[10:11], 0.5, v[42:43] op_sel_hi:[1,0,1]
	v_pk_fma_f32 v[8:9], v[8:9], 0.5, v[40:41] op_sel_hi:[1,0,1]
	v_fmac_f32_e32 v20, v14, v14
	global_store_dwordx4 v[18:19], v[8:11], off offset:64
	v_or_b32_e32 v12, 32, v16
	v_mov_b32_e32 v13, v17
	v_cvt_pk_bf16_f32 v14, v8, v9
	v_mul_f32_e32 v8, v8, v8
	v_lshl_add_u64 v[12:13], s[0:1], 0, v[12:13]
	v_fmac_f32_e32 v8, v9, v9
	v_pk_fma_f32 v[6:7], v[6:7], 0.5, v[38:39] op_sel_hi:[1,0,1]
	v_pk_fma_f32 v[4:5], v[4:5], 0.5, v[36:37] op_sel_hi:[1,0,1]
	v_fmac_f32_e32 v20, v15, v15
	v_cvt_pk_bf16_f32 v15, v10, v11
	v_mov_b32_e32 v242, v14
	v_mov_b32_e32 v243, v15
	s_nop 1
	v_permlane16_swap_b32 v240, v242
	v_permlane16_swap_b32 v241, v243
	global_store_dwordx4 v[244:245], v[240:243], off
	v_fmac_f32_e32 v8, v10, v10
	global_store_dwordx4 v[18:19], v[4:7], off offset:512
	v_cvt_pk_bf16_f32 v10, v4, v5
	v_fmac_f32_e32 v8, v11, v11
	v_add_f32_e32 v11, v20, v8
	v_mul_f32_e32 v4, v4, v4
	v_fmac_f32_e32 v4, v5, v5
	v_fmac_f32_e32 v4, v6, v6
	v_fmac_f32_e32 v4, v7, v7
	v_add_f32_e32 v11, v11, v4
	v_pk_fma_f32 v[4:5], v[2:3], 0.5, v[34:35] op_sel_hi:[1,0,1]
	v_pk_fma_f32 v[2:3], v[0:1], 0.5, v[32:33] op_sel_hi:[1,0,1]
	v_or_b32_e32 v8, 0x100, v16
	v_mul_f32_e32 v0, v2, v2
	v_fmac_f32_e32 v0, v3, v3
	v_fmac_f32_e32 v0, v4, v4
	v_fmac_f32_e32 v0, v5, v5
	v_add_f32_e32 v0, v11, v0
	ds_bpermute_b32 v1, v116, v0
	v_mov_b32_e32 v9, v17
	v_or_b32_e32 v16, 0x120, v16
	v_lshl_add_u64 v[8:9], s[0:1], 0, v[8:9]
	v_cvt_pk_bf16_f32 v11, v6, v7
	s_waitcnt lgkmcnt(0)
	v_add_f32_e32 v0, v0, v1
	ds_bpermute_b32 v1, v117, v0
	v_lshl_add_u64 v[6:7], s[0:1], 0, v[16:17]
	s_nop 1
	v_mov_b32_e32 v240, v10
	v_mov_b32_e32 v241, v11
	v_lshl_add_u64 v[244:245], v[8:9], 0, v[246:247]
	global_store_dwordx4 v[18:19], v[2:5], off offset:576
	s_nop 1
	v_cvt_pk_bf16_f32 v2, v2, v3
	v_cvt_pk_bf16_f32 v3, v4, v5
	v_mov_b32_e32 v242, v2
	v_mov_b32_e32 v243, v3
	s_nop 1
	v_permlane16_swap_b32 v240, v242
	v_permlane16_swap_b32 v241, v243
	global_store_dwordx4 v[244:245], v[240:243], off
	s_and_saveexec_b64 s[36:37], s[8:9]
	s_cbranch_execz .LBB0_385
	v_lshlrev_b64 v[2:3], 6, v[48:49]
	v_lshl_add_u64 v[2:3], s[2:3], 0, v[2:3]
	v_lshl_add_u64 v[2:3], s[16:17], 2, v[2:3]
	s_lshl_b32 s6, s83, 2
	v_lshl_add_u64 v[2:3], v[2:3], 0, s[6:7]
	s_waitcnt lgkmcnt(0)
	v_add_f32_e32 v0, v0, v1
	v_mov_b32_e32 v236, v2
	v_mov_b32_e32 v237, v3
	v_mov_b32_e32 v238, v0
	s_or_b64 exec, exec, s[36:37]
	s_nop 4
	v_permlane16_swap_b32 v236, v232
	v_permlane16_swap_b32 v237, v233
	v_permlane16_swap_b32 v238, v234
	s_mov_b64 s[36:37], exec
	s_mov_b64 exec, 0xffffffff
	global_store_dword v[236:237], v238, off
	s_mov_b64 exec, s[36:37]
	s_branch .LBB0_385

.LBB0_1493:
	s_or_b64 exec, exec, s[30:31]
	s_nop 4
	v_permlane16_swap_b32 v236, v232
	v_permlane16_swap_b32 v237, v233
	v_permlane16_swap_b32 v238, v234
	s_mov_b64 s[30:31], exec
	s_mov_b64 exec, 0xffffffff
	global_store_dword v[236:237], v238, off
	s_mov_b64 exec, s[30:31]
	v_lshl_add_u64 v[50:51], v[164:165], 0, s[16:17]
	s_waitcnt lgkmcnt(0)
	v_lshlrev_b64 v[32:33], 12, v[50:51]
	v_lshl_add_u64 v[32:33], v[166:167], 0, v[32:33]
	global_load_dwordx4 v[52:55], v[32:33], off
	global_load_dwordx4 v[56:59], v[32:33], off offset:64
	global_load_dwordx4 v[60:63], v[32:33], off offset:512
	global_load_dwordx4 v[64:67], v[32:33], off offset:576
	v_lshl_add_u64 v[48:49], v[164:165], 0, s[18:19]
	v_lshlrev_b64 v[32:33], 12, v[48:49]
	v_lshl_add_u64 v[32:33], v[166:167], 0, v[32:33]
	global_load_dwordx4 v[44:47], v[32:33], off
	global_load_dwordx4 v[40:43], v[32:33], off offset:64
	global_load_dwordx4 v[36:39], v[32:33], off offset:512
	s_nop 0
	global_load_dwordx4 v[32:35], v[32:33], off offset:576
	v_lshlrev_b64 v[68:69], 10, v[50:51]
	v_lshl_add_u64 v[68:69], v[68:69], 0, v[162:163]
	v_lshl_add_u64 v[70:71], v[68:69], 2, s[78:79]
	v_lshlrev_b64 v[68:69], 1, v[68:69]
	v_lshl_add_u64 v[72:73], s[2:3], 0, v[68:69]
	s_waitcnt vmcnt(0)
	v_or_b32_e32 v74, 32, v68
	v_mov_b32_e32 v75, v69
	v_or_b32_e32 v76, 0x100, v68
	v_mov_b32_e32 v77, v69
	v_or_b32_e32 v68, 0x120, v68
	v_lshl_add_u64 v[74:75], s[2:3], 0, v[74:75]
	v_lshl_add_u64 v[76:77], s[2:3], 0, v[76:77]
	s_waitcnt vmcnt(0)
	v_pk_add_f32 v[28:29], v[28:29], v[52:53]
	v_pk_add_f32 v[24:25], v[24:25], v[56:57]
	v_pk_add_f32 v[20:21], v[20:21], v[60:61]
	v_mul_f32_e32 v56, v28, v28
	v_mul_f32_e32 v57, v24, v24
	v_pk_add_f32 v[30:31], v[30:31], v[54:55]
	v_pk_add_f32 v[26:27], v[26:27], v[58:59]
	v_pk_add_f32 v[52:53], v[16:17], v[64:65]
	v_mul_f32_e32 v58, v20, v20
	v_fmac_f32_e32 v56, v29, v29
	v_fmac_f32_e32 v57, v25, v25
	v_pk_add_f32 v[22:23], v[22:23], v[62:63]
	v_mul_f32_e32 v59, v52, v52
	v_fmac_f32_e32 v58, v21, v21
	v_fmac_f32_e32 v56, v30, v30
	v_fmac_f32_e32 v57, v26, v26
	v_pk_add_f32 v[54:55], v[18:19], v[66:67]
	v_cvt_pk_bf16_f32 v16, v28, v29
	v_fmac_f32_e32 v59, v53, v53
	v_fmac_f32_e32 v58, v22, v22
	v_fmac_f32_e32 v56, v31, v31
	v_fmac_f32_e32 v57, v27, v27
	global_store_dwordx4 v[70:71], v[28:31], off
	v_cvt_pk_bf16_f32 v17, v30, v31
	s_nop 1
	v_mov_b32_e32 v240, v16
	v_mov_b32_e32 v241, v17
	v_lshl_add_u64 v[244:245], v[72:73], 0, v[246:247]
	v_fmac_f32_e32 v59, v54, v54
	v_fmac_f32_e32 v58, v23, v23
	v_add_f32_e32 v16, v56, v57
	v_add_f32_e32 v16, v16, v58
	v_fmac_f32_e32 v59, v55, v55
	v_add_f32_e32 v16, v16, v59
	ds_bpermute_b32 v17, v189, v16
	v_cvt_pk_bf16_f32 v18, v24, v25
	v_cvt_pk_bf16_f32 v19, v26, v27
	v_cvt_pk_bf16_f32 v28, v20, v21
	global_store_dwordx4 v[70:71], v[24:27], off offset:64
	v_mov_b32_e32 v242, v18
	v_mov_b32_e32 v243, v19
	s_nop 1
	v_permlane16_swap_b32 v240, v242
	v_permlane16_swap_b32 v241, v243
	global_store_dwordx4 v[244:245], v[240:243], off
	s_waitcnt lgkmcnt(0)
	v_add_f32_e32 v16, v16, v17
	ds_bpermute_b32 v17, v116, v16
	v_cvt_pk_bf16_f32 v29, v22, v23
	v_lshl_add_u64 v[18:19], s[2:3], 0, v[68:69]
	global_store_dwordx4 v[70:71], v[20:23], off offset:512
	s_nop 1
	v_mov_b32_e32 v240, v28
	v_mov_b32_e32 v241, v29
	v_lshl_add_u64 v[244:245], v[76:77], 0, v[246:247]
	global_store_dwordx4 v[70:71], v[52:55], off offset:576
	v_cvt_pk_bf16_f32 v20, v52, v53
	v_cvt_pk_bf16_f32 v21, v54, v55
	v_mov_b32_e32 v242, v20
	v_mov_b32_e32 v243, v21
	s_nop 1
	v_permlane16_swap_b32 v240, v242
	v_permlane16_swap_b32 v241, v243
	global_store_dwordx4 v[244:245], v[240:243], off
	s_and_saveexec_b64 s[30:31], s[6:7]
	s_cbranch_execz .LBB0_1495
	v_lshlrev_b64 v[18:19], 6, v[50:51]
	v_lshl_add_u64 v[18:19], s[4:5], 0, v[18:19]
	v_lshl_add_u64 v[18:19], s[28:29], 2, v[18:19]
	s_lshl_b32 s12, s55, 2
	v_lshl_add_u64 v[18:19], v[18:19], 0, s[12:13]
	s_waitcnt lgkmcnt(0)
	v_add_f32_e32 v16, v16, v17
	v_mov_b32_e32 v232, v18
	v_mov_b32_e32 v233, v19
	v_mov_b32_e32 v234, v16
.LBB0_1495:
	s_or_b64 exec, exec, s[30:31]
	s_waitcnt lgkmcnt(0)
	v_lshlrev_b64 v[16:17], 10, v[48:49]
	v_lshl_add_u64 v[16:17], v[16:17], 0, v[162:163]
	v_lshl_add_u64 v[18:19], v[16:17], 2, s[78:79]
	v_lshlrev_b64 v[16:17], 1, v[16:17]
	v_pk_add_f32 v[14:15], v[14:15], v[46:47]
	v_pk_add_f32 v[12:13], v[12:13], v[44:45]
	v_lshl_add_u64 v[20:21], s[2:3], 0, v[16:17]
	global_store_dwordx4 v[18:19], v[12:15], off
	v_cvt_pk_bf16_f32 v22, v12, v13
	v_cvt_pk_bf16_f32 v23, v14, v15
	s_nop 1
	v_mov_b32_e32 v240, v22
	v_mov_b32_e32 v241, v23
	v_lshl_add_u64 v[244:245], v[20:21], 0, v[246:247]
	v_mul_f32_e32 v20, v12, v12
	v_fmac_f32_e32 v20, v13, v13
	v_pk_add_f32 v[10:11], v[10:11], v[42:43]
	v_pk_add_f32 v[8:9], v[8:9], v[40:41]
	v_fmac_f32_e32 v20, v14, v14
	global_store_dwordx4 v[18:19], v[8:11], off offset:64
	v_or_b32_e32 v12, 32, v16
	v_mov_b32_e32 v13, v17
	v_cvt_pk_bf16_f32 v14, v8, v9
	v_mul_f32_e32 v8, v8, v8
	v_lshl_add_u64 v[12:13], s[2:3], 0, v[12:13]
	v_fmac_f32_e32 v8, v9, v9
	v_pk_add_f32 v[6:7], v[6:7], v[38:39]
	v_pk_add_f32 v[4:5], v[4:5], v[36:37]
	v_fmac_f32_e32 v20, v15, v15
	v_cvt_pk_bf16_f32 v15, v10, v11
	v_mov_b32_e32 v242, v14
	v_mov_b32_e32 v243, v15
	s_nop 1
	v_permlane16_swap_b32 v240, v242
	v_permlane16_swap_b32 v241, v243
	global_store_dwordx4 v[244:245], v[240:243], off
	v_fmac_f32_e32 v8, v10, v10
	global_store_dwordx4 v[18:19], v[4:7], off offset:512
	v_cvt_pk_bf16_f32 v10, v4, v5
	v_fmac_f32_e32 v8, v11, v11
	v_add_f32_e32 v11, v20, v8
	v_mul_f32_e32 v4, v4, v4
	v_fmac_f32_e32 v4, v5, v5
	v_fmac_f32_e32 v4, v6, v6
	v_fmac_f32_e32 v4, v7, v7
	v_add_f32_e32 v11, v11, v4
	v_pk_add_f32 v[4:5], v[2:3], v[34:35]
	v_pk_add_f32 v[2:3], v[0:1], v[32:33]
	v_or_b32_e32 v8, 0x100, v16
	v_mul_f32_e32 v0, v2, v2
	v_fmac_f32_e32 v0, v3, v3
	v_fmac_f32_e32 v0, v4, v4
	v_fmac_f32_e32 v0, v5, v5
	v_add_f32_e32 v0, v11, v0
	ds_bpermute_b32 v1, v189, v0
	v_mov_b32_e32 v9, v17
	v_or_b32_e32 v16, 0x120, v16
	v_lshl_add_u64 v[8:9], s[2:3], 0, v[8:9]
	v_cvt_pk_bf16_f32 v11, v6, v7
	s_waitcnt lgkmcnt(0)
	v_add_f32_e32 v0, v0, v1
	ds_bpermute_b32 v1, v116, v0
	v_lshl_add_u64 v[6:7], s[2:3], 0, v[16:17]
	s_nop 1
	v_mov_b32_e32 v240, v10
	v_mov_b32_e32 v241, v11
	v_lshl_add_u64 v[244:245], v[8:9], 0, v[246:247]
	global_store_dwordx4 v[18:19], v[2:5], off offset:576
	s_nop 1
	v_cvt_pk_bf16_f32 v2, v2, v3
	v_cvt_pk_bf16_f32 v3, v4, v5
	v_mov_b32_e32 v242, v2
	v_mov_b32_e32 v243, v3
	s_nop 1
	v_permlane16_swap_b32 v240, v242
	v_permlane16_swap_b32 v241, v243
	global_store_dwordx4 v[244:245], v[240:243], off
	s_and_saveexec_b64 s[30:31], s[6:7]
	s_cbranch_execz .LBB0_1472
	v_lshlrev_b64 v[2:3], 6, v[48:49]
	v_lshl_add_u64 v[2:3], s[4:5], 0, v[2:3]
	v_lshl_add_u64 v[2:3], s[28:29], 2, v[2:3]
	s_lshl_b32 s12, s55, 2
	v_lshl_add_u64 v[2:3], v[2:3], 0, s[12:13]
	s_waitcnt lgkmcnt(0)
	v_add_f32_e32 v0, v0, v1
	v_mov_b32_e32 v236, v2
	v_mov_b32_e32 v237, v3
	v_mov_b32_e32 v238, v0
	s_or_b64 exec, exec, s[30:31]
	s_nop 4
	v_permlane16_swap_b32 v236, v232
	v_permlane16_swap_b32 v237, v233
	v_permlane16_swap_b32 v238, v234
	s_mov_b64 s[30:31], exec
	s_mov_b64 exec, 0xffffffff
	global_store_dword v[236:237], v238, off
	s_mov_b64 exec, s[30:31]
	s_branch .LBB0_1472

.LBB0_1655:
	s_or_b64 exec, exec, s[26:27]
	s_nop 4
	v_permlane16_swap_b32 v236, v232
	v_permlane16_swap_b32 v237, v233
	v_permlane16_swap_b32 v238, v234
	s_mov_b64 s[26:27], exec
	s_mov_b64 exec, 0xffffffff
	global_store_dword v[236:237], v238, off
	s_mov_b64 exec, s[26:27]
	v_lshl_add_u64 v[50:51], v[164:165], 0, s[20:21]
	s_waitcnt lgkmcnt(0)
	v_lshlrev_b64 v[32:33], 12, v[50:51]
	v_lshl_add_u64 v[32:33], v[166:167], 0, v[32:33]
	global_load_dwordx4 v[52:55], v[32:33], off
	global_load_dwordx4 v[56:59], v[32:33], off offset:64
	global_load_dwordx4 v[60:63], v[32:33], off offset:512
	global_load_dwordx4 v[64:67], v[32:33], off offset:576
	v_lshl_add_u64 v[48:49], v[164:165], 0, s[22:23]
	v_lshlrev_b64 v[32:33], 12, v[48:49]
	v_lshl_add_u64 v[32:33], v[166:167], 0, v[32:33]
	global_load_dwordx4 v[44:47], v[32:33], off
	global_load_dwordx4 v[40:43], v[32:33], off offset:64
	global_load_dwordx4 v[36:39], v[32:33], off offset:512
	s_nop 0
	global_load_dwordx4 v[32:35], v[32:33], off offset:576
	v_lshlrev_b64 v[68:69], 10, v[50:51]
	v_lshl_add_u64 v[68:69], v[68:69], 0, v[162:163]
	v_lshl_add_u64 v[70:71], v[68:69], 2, s[78:79]
	v_lshlrev_b64 v[68:69], 1, v[68:69]
	v_lshl_add_u64 v[72:73], s[2:3], 0, v[68:69]
	s_waitcnt vmcnt(0)
	v_or_b32_e32 v74, 32, v68
	v_mov_b32_e32 v75, v69
	v_or_b32_e32 v76, 0x100, v68
	v_mov_b32_e32 v77, v69
	v_or_b32_e32 v68, 0x120, v68
	v_lshl_add_u64 v[74:75], s[2:3], 0, v[74:75]
	v_lshl_add_u64 v[76:77], s[2:3], 0, v[76:77]
	s_waitcnt vmcnt(0)
	v_pk_fma_f32 v[28:29], v[28:29], 0.5, v[52:53] op_sel_hi:[1,0,1]
	v_pk_fma_f32 v[24:25], v[24:25], 0.5, v[56:57] op_sel_hi:[1,0,1]
	v_pk_fma_f32 v[20:21], v[20:21], 0.5, v[60:61] op_sel_hi:[1,0,1]
	v_mul_f32_e32 v56, v28, v28
	v_mul_f32_e32 v57, v24, v24
	v_pk_fma_f32 v[30:31], v[30:31], 0.5, v[54:55] op_sel_hi:[1,0,1]
	v_pk_fma_f32 v[26:27], v[26:27], 0.5, v[58:59] op_sel_hi:[1,0,1]
	v_pk_fma_f32 v[52:53], v[16:17], 0.5, v[64:65] op_sel_hi:[1,0,1]
	v_mul_f32_e32 v58, v20, v20
	v_fmac_f32_e32 v56, v29, v29
	v_fmac_f32_e32 v57, v25, v25
	v_pk_fma_f32 v[22:23], v[22:23], 0.5, v[62:63] op_sel_hi:[1,0,1]
	v_mul_f32_e32 v59, v52, v52
	v_fmac_f32_e32 v58, v21, v21
	v_fmac_f32_e32 v56, v30, v30
	v_fmac_f32_e32 v57, v26, v26
	v_pk_fma_f32 v[54:55], v[18:19], 0.5, v[66:67] op_sel_hi:[1,0,1]
	v_cvt_pk_bf16_f32 v16, v28, v29
	v_fmac_f32_e32 v59, v53, v53
	v_fmac_f32_e32 v58, v22, v22
	v_fmac_f32_e32 v56, v31, v31
	v_fmac_f32_e32 v57, v27, v27
	global_store_dwordx4 v[70:71], v[28:31], off
	v_cvt_pk_bf16_f32 v17, v30, v31
	s_nop 1
	v_mov_b32_e32 v240, v16
	v_mov_b32_e32 v241, v17
	v_lshl_add_u64 v[244:245], v[72:73], 0, v[246:247]
	v_fmac_f32_e32 v59, v54, v54
	v_fmac_f32_e32 v58, v23, v23
	v_add_f32_e32 v16, v56, v57
	v_add_f32_e32 v16, v16, v58
	v_fmac_f32_e32 v59, v55, v55
	v_add_f32_e32 v16, v16, v59
	ds_bpermute_b32 v17, v189, v16
	v_cvt_pk_bf16_f32 v18, v24, v25
	v_cvt_pk_bf16_f32 v19, v26, v27
	v_cvt_pk_bf16_f32 v28, v20, v21
	global_store_dwordx4 v[70:71], v[24:27], off offset:64
	v_mov_b32_e32 v242, v18
	v_mov_b32_e32 v243, v19
	s_nop 1
	v_permlane16_swap_b32 v240, v242
	v_permlane16_swap_b32 v241, v243
	global_store_dwordx4 v[244:245], v[240:243], off
	s_waitcnt lgkmcnt(0)
	v_add_f32_e32 v16, v16, v17
	ds_bpermute_b32 v17, v116, v16
	v_cvt_pk_bf16_f32 v29, v22, v23
	v_lshl_add_u64 v[18:19], s[2:3], 0, v[68:69]
	global_store_dwordx4 v[70:71], v[20:23], off offset:512
	s_nop 1
	v_mov_b32_e32 v240, v28
	v_mov_b32_e32 v241, v29
	v_lshl_add_u64 v[244:245], v[76:77], 0, v[246:247]
	global_store_dwordx4 v[70:71], v[52:55], off offset:576
	v_cvt_pk_bf16_f32 v20, v52, v53
	v_cvt_pk_bf16_f32 v21, v54, v55
	v_mov_b32_e32 v242, v20
	v_mov_b32_e32 v243, v21
	s_nop 1
	v_permlane16_swap_b32 v240, v242
	v_permlane16_swap_b32 v241, v243
	global_store_dwordx4 v[244:245], v[240:243], off
	s_and_saveexec_b64 s[26:27], s[6:7]
	s_cbranch_execz .LBB0_1657
	v_lshlrev_b64 v[18:19], 6, v[50:51]
	v_lshl_add_u64 v[18:19], s[4:5], 0, v[18:19]
	v_lshl_add_u64 v[18:19], s[24:25], 2, v[18:19]
	s_lshl_b32 s16, s49, 2
	v_lshl_add_u64 v[18:19], v[18:19], 0, s[16:17]
	s_waitcnt lgkmcnt(0)
	v_add_f32_e32 v16, v16, v17
	v_mov_b32_e32 v232, v18
	v_mov_b32_e32 v233, v19
	v_mov_b32_e32 v234, v16
.LBB0_1657:
	s_or_b64 exec, exec, s[26:27]
	s_waitcnt lgkmcnt(0)
	v_lshlrev_b64 v[16:17], 10, v[48:49]
	v_lshl_add_u64 v[16:17], v[16:17], 0, v[162:163]
	v_lshl_add_u64 v[18:19], v[16:17], 2, s[78:79]
	v_lshlrev_b64 v[16:17], 1, v[16:17]
	v_pk_fma_f32 v[14:15], v[14:15], 0.5, v[46:47] op_sel_hi:[1,0,1]
	v_pk_fma_f32 v[12:13], v[12:13], 0.5, v[44:45] op_sel_hi:[1,0,1]
	v_lshl_add_u64 v[20:21], s[2:3], 0, v[16:17]
	global_store_dwordx4 v[18:19], v[12:15], off
	v_cvt_pk_bf16_f32 v22, v12, v13
	v_cvt_pk_bf16_f32 v23, v14, v15
	s_nop 1
	v_mov_b32_e32 v240, v22
	v_mov_b32_e32 v241, v23
	v_lshl_add_u64 v[244:245], v[20:21], 0, v[246:247]
	v_mul_f32_e32 v20, v12, v12
	v_fmac_f32_e32 v20, v13, v13
	v_pk_fma_f32 v[10:11], v[10:11], 0.5, v[42:43] op_sel_hi:[1,0,1]
	v_pk_fma_f32 v[8:9], v[8:9], 0.5, v[40:41] op_sel_hi:[1,0,1]
	v_fmac_f32_e32 v20, v14, v14
	global_store_dwordx4 v[18:19], v[8:11], off offset:64
	v_or_b32_e32 v12, 32, v16
	v_mov_b32_e32 v13, v17
	v_cvt_pk_bf16_f32 v14, v8, v9
	v_mul_f32_e32 v8, v8, v8
	v_lshl_add_u64 v[12:13], s[2:3], 0, v[12:13]
	v_fmac_f32_e32 v8, v9, v9
	v_pk_fma_f32 v[6:7], v[6:7], 0.5, v[38:39] op_sel_hi:[1,0,1]
	v_pk_fma_f32 v[4:5], v[4:5], 0.5, v[36:37] op_sel_hi:[1,0,1]
	v_fmac_f32_e32 v20, v15, v15
	v_cvt_pk_bf16_f32 v15, v10, v11
	v_mov_b32_e32 v242, v14
	v_mov_b32_e32 v243, v15
	s_nop 1
	v_permlane16_swap_b32 v240, v242
	v_permlane16_swap_b32 v241, v243
	global_store_dwordx4 v[244:245], v[240:243], off
	v_fmac_f32_e32 v8, v10, v10
	global_store_dwordx4 v[18:19], v[4:7], off offset:512
	v_cvt_pk_bf16_f32 v10, v4, v5
	v_fmac_f32_e32 v8, v11, v11
	v_add_f32_e32 v11, v20, v8
	v_mul_f32_e32 v4, v4, v4
	v_fmac_f32_e32 v4, v5, v5
	v_fmac_f32_e32 v4, v6, v6
	v_fmac_f32_e32 v4, v7, v7
	v_add_f32_e32 v11, v11, v4
	v_pk_fma_f32 v[4:5], v[2:3], 0.5, v[34:35] op_sel_hi:[1,0,1]
	v_pk_fma_f32 v[2:3], v[0:1], 0.5, v[32:33] op_sel_hi:[1,0,1]
	v_or_b32_e32 v8, 0x100, v16
	v_mul_f32_e32 v0, v2, v2
	v_fmac_f32_e32 v0, v3, v3
	v_fmac_f32_e32 v0, v4, v4
	v_fmac_f32_e32 v0, v5, v5
	v_add_f32_e32 v0, v11, v0
	ds_bpermute_b32 v1, v189, v0
	v_mov_b32_e32 v9, v17
	v_or_b32_e32 v16, 0x120, v16
	v_lshl_add_u64 v[8:9], s[2:3], 0, v[8:9]
	v_cvt_pk_bf16_f32 v11, v6, v7
	s_waitcnt lgkmcnt(0)
	v_add_f32_e32 v0, v0, v1
	ds_bpermute_b32 v1, v116, v0
	v_lshl_add_u64 v[6:7], s[2:3], 0, v[16:17]
	s_nop 1
	v_mov_b32_e32 v240, v10
	v_mov_b32_e32 v241, v11
	v_lshl_add_u64 v[244:245], v[8:9], 0, v[246:247]
	global_store_dwordx4 v[18:19], v[2:5], off offset:576
	s_nop 1
	v_cvt_pk_bf16_f32 v2, v2, v3
	v_cvt_pk_bf16_f32 v3, v4, v5
	v_mov_b32_e32 v242, v2
	v_mov_b32_e32 v243, v3
	s_nop 1
	v_permlane16_swap_b32 v240, v242
	v_permlane16_swap_b32 v241, v243
	global_store_dwordx4 v[244:245], v[240:243], off
	s_and_saveexec_b64 s[26:27], s[6:7]
	s_cbranch_execz .LBB0_1630
	v_lshlrev_b64 v[2:3], 6, v[48:49]
	v_lshl_add_u64 v[2:3], s[4:5], 0, v[2:3]
	v_lshl_add_u64 v[2:3], s[24:25], 2, v[2:3]
	s_lshl_b32 s16, s49, 2
	v_lshl_add_u64 v[2:3], v[2:3], 0, s[16:17]
	s_waitcnt lgkmcnt(0)
	v_add_f32_e32 v0, v0, v1
	v_mov_b32_e32 v236, v2
	v_mov_b32_e32 v237, v3
	v_mov_b32_e32 v238, v0
	s_or_b64 exec, exec, s[26:27]
	s_nop 4
	v_permlane16_swap_b32 v236, v232
	v_permlane16_swap_b32 v237, v233
	v_permlane16_swap_b32 v238, v234
	s_mov_b64 s[26:27], exec
	s_mov_b64 exec, 0xffffffff
	global_store_dword v[236:237], v238, off
	s_mov_b64 exec, s[26:27]
	s_branch .LBB0_1630

.LBB0_1825:
	s_or_b64 exec, exec, s[28:29]
	s_nop 4
	v_permlane16_swap_b32 v236, v232
	v_permlane16_swap_b32 v237, v233
	v_permlane16_swap_b32 v238, v234
	s_mov_b64 s[28:29], exec
	s_mov_b64 exec, 0xffffffff
	global_store_dword v[236:237], v238, off
	s_mov_b64 exec, s[28:29]
	v_lshl_add_u64 v[50:51], v[164:165], 0, s[22:23]
	s_waitcnt lgkmcnt(0)
	v_lshlrev_b64 v[32:33], 12, v[50:51]
	v_lshl_add_u64 v[32:33], v[166:167], 0, v[32:33]
	global_load_dwordx4 v[52:55], v[32:33], off
	global_load_dwordx4 v[56:59], v[32:33], off offset:64
	global_load_dwordx4 v[60:63], v[32:33], off offset:512
	global_load_dwordx4 v[64:67], v[32:33], off offset:576
	v_lshl_add_u64 v[48:49], v[164:165], 0, s[24:25]
	v_lshlrev_b64 v[32:33], 12, v[48:49]
	v_lshl_add_u64 v[32:33], v[166:167], 0, v[32:33]
	global_load_dwordx4 v[44:47], v[32:33], off
	global_load_dwordx4 v[40:43], v[32:33], off offset:64
	global_load_dwordx4 v[36:39], v[32:33], off offset:512
	s_nop 0
	global_load_dwordx4 v[32:35], v[32:33], off offset:576
	v_lshlrev_b64 v[68:69], 10, v[50:51]
	v_lshl_add_u64 v[68:69], v[68:69], 0, v[162:163]
	v_lshl_add_u64 v[70:71], v[68:69], 2, s[78:79]
	v_lshlrev_b64 v[68:69], 1, v[68:69]
	v_lshl_add_u64 v[72:73], s[4:5], 0, v[68:69]
	s_waitcnt vmcnt(0)
	v_or_b32_e32 v74, 32, v68
	v_mov_b32_e32 v75, v69
	v_or_b32_e32 v76, 0x100, v68
	v_mov_b32_e32 v77, v69
	v_or_b32_e32 v68, 0x120, v68
	v_lshl_add_u64 v[74:75], s[4:5], 0, v[74:75]
	v_lshl_add_u64 v[76:77], s[4:5], 0, v[76:77]
	s_waitcnt vmcnt(0)
	v_pk_fma_f32 v[28:29], v[28:29], 0.5, v[52:53] op_sel_hi:[1,0,1]
	v_pk_fma_f32 v[24:25], v[24:25], 0.5, v[56:57] op_sel_hi:[1,0,1]
	v_pk_fma_f32 v[20:21], v[20:21], 0.5, v[60:61] op_sel_hi:[1,0,1]
	v_mul_f32_e32 v56, v28, v28
	v_mul_f32_e32 v57, v24, v24
	v_pk_fma_f32 v[30:31], v[30:31], 0.5, v[54:55] op_sel_hi:[1,0,1]
	v_pk_fma_f32 v[26:27], v[26:27], 0.5, v[58:59] op_sel_hi:[1,0,1]
	v_pk_fma_f32 v[52:53], v[16:17], 0.5, v[64:65] op_sel_hi:[1,0,1]
	v_mul_f32_e32 v58, v20, v20
	v_fmac_f32_e32 v56, v29, v29
	v_fmac_f32_e32 v57, v25, v25
	v_pk_fma_f32 v[22:23], v[22:23], 0.5, v[62:63] op_sel_hi:[1,0,1]
	v_mul_f32_e32 v59, v52, v52
	v_fmac_f32_e32 v58, v21, v21
	v_fmac_f32_e32 v56, v30, v30
	v_fmac_f32_e32 v57, v26, v26
	v_pk_fma_f32 v[54:55], v[18:19], 0.5, v[66:67] op_sel_hi:[1,0,1]
	v_cvt_pk_bf16_f32 v16, v28, v29
	v_fmac_f32_e32 v59, v53, v53
	v_fmac_f32_e32 v58, v22, v22
	v_fmac_f32_e32 v56, v31, v31
	v_fmac_f32_e32 v57, v27, v27
	global_store_dwordx4 v[70:71], v[28:31], off
	v_cvt_pk_bf16_f32 v17, v30, v31
	s_nop 1
	v_mov_b32_e32 v240, v16
	v_mov_b32_e32 v241, v17
	v_lshl_add_u64 v[244:245], v[72:73], 0, v[246:247]
	v_fmac_f32_e32 v59, v54, v54
	v_fmac_f32_e32 v58, v23, v23
	v_add_f32_e32 v16, v56, v57
	v_add_f32_e32 v16, v16, v58
	v_fmac_f32_e32 v59, v55, v55
	v_add_f32_e32 v16, v16, v59
	ds_bpermute_b32 v17, v192, v16
	v_cvt_pk_bf16_f32 v18, v24, v25
	v_cvt_pk_bf16_f32 v19, v26, v27
	v_cvt_pk_bf16_f32 v28, v20, v21
	global_store_dwordx4 v[70:71], v[24:27], off offset:64
	v_mov_b32_e32 v242, v18
	v_mov_b32_e32 v243, v19
	s_nop 1
	v_permlane16_swap_b32 v240, v242
	v_permlane16_swap_b32 v241, v243
	global_store_dwordx4 v[244:245], v[240:243], off
	s_waitcnt lgkmcnt(0)
	v_add_f32_e32 v16, v16, v17
	ds_bpermute_b32 v17, v116, v16
	v_cvt_pk_bf16_f32 v29, v22, v23
	v_lshl_add_u64 v[18:19], s[4:5], 0, v[68:69]
	global_store_dwordx4 v[70:71], v[20:23], off offset:512
	s_nop 1
	v_mov_b32_e32 v240, v28
	v_mov_b32_e32 v241, v29
	v_lshl_add_u64 v[244:245], v[76:77], 0, v[246:247]
	global_store_dwordx4 v[70:71], v[52:55], off offset:576
	v_cvt_pk_bf16_f32 v20, v52, v53
	v_cvt_pk_bf16_f32 v21, v54, v55
	v_mov_b32_e32 v242, v20
	v_mov_b32_e32 v243, v21
	s_nop 1
	v_permlane16_swap_b32 v240, v242
	v_permlane16_swap_b32 v241, v243
	global_store_dwordx4 v[244:245], v[240:243], off
	s_and_saveexec_b64 s[28:29], s[6:7]
	s_cbranch_execz .LBB0_1827
	v_lshlrev_b64 v[18:19], 6, v[50:51]
	v_lshl_add_u64 v[18:19], s[14:15], 0, v[18:19]
	v_lshl_add_u64 v[18:19], s[26:27], 2, v[18:19]
	s_lshl_b32 s18, s53, 2
	v_lshl_add_u64 v[18:19], v[18:19], 0, s[18:19]
	s_waitcnt lgkmcnt(0)
	v_add_f32_e32 v16, v16, v17
	v_mov_b32_e32 v232, v18
	v_mov_b32_e32 v233, v19
	v_mov_b32_e32 v234, v16
.LBB0_1827:
	s_or_b64 exec, exec, s[28:29]
	s_waitcnt lgkmcnt(0)
	v_lshlrev_b64 v[16:17], 10, v[48:49]
	v_lshl_add_u64 v[16:17], v[16:17], 0, v[162:163]
	v_lshl_add_u64 v[18:19], v[16:17], 2, s[78:79]
	v_lshlrev_b64 v[16:17], 1, v[16:17]
	v_pk_fma_f32 v[14:15], v[14:15], 0.5, v[46:47] op_sel_hi:[1,0,1]
	v_pk_fma_f32 v[12:13], v[12:13], 0.5, v[44:45] op_sel_hi:[1,0,1]
	v_lshl_add_u64 v[20:21], s[4:5], 0, v[16:17]
	global_store_dwordx4 v[18:19], v[12:15], off
	v_cvt_pk_bf16_f32 v22, v12, v13
	v_cvt_pk_bf16_f32 v23, v14, v15
	s_nop 1
	v_mov_b32_e32 v240, v22
	v_mov_b32_e32 v241, v23
	v_lshl_add_u64 v[244:245], v[20:21], 0, v[246:247]
	v_mul_f32_e32 v20, v12, v12
	v_fmac_f32_e32 v20, v13, v13
	v_pk_fma_f32 v[10:11], v[10:11], 0.5, v[42:43] op_sel_hi:[1,0,1]
	v_pk_fma_f32 v[8:9], v[8:9], 0.5, v[40:41] op_sel_hi:[1,0,1]
	v_fmac_f32_e32 v20, v14, v14
	global_store_dwordx4 v[18:19], v[8:11], off offset:64
	v_or_b32_e32 v12, 32, v16
	v_mov_b32_e32 v13, v17
	v_cvt_pk_bf16_f32 v14, v8, v9
	v_mul_f32_e32 v8, v8, v8
	v_lshl_add_u64 v[12:13], s[4:5], 0, v[12:13]
	v_fmac_f32_e32 v8, v9, v9
	v_pk_fma_f32 v[6:7], v[6:7], 0.5, v[38:39] op_sel_hi:[1,0,1]
	v_pk_fma_f32 v[4:5], v[4:5], 0.5, v[36:37] op_sel_hi:[1,0,1]
	v_fmac_f32_e32 v20, v15, v15
	v_cvt_pk_bf16_f32 v15, v10, v11
	v_mov_b32_e32 v242, v14
	v_mov_b32_e32 v243, v15
	s_nop 1
	v_permlane16_swap_b32 v240, v242
	v_permlane16_swap_b32 v241, v243
	global_store_dwordx4 v[244:245], v[240:243], off
	v_fmac_f32_e32 v8, v10, v10
	global_store_dwordx4 v[18:19], v[4:7], off offset:512
	v_cvt_pk_bf16_f32 v10, v4, v5
	v_fmac_f32_e32 v8, v11, v11
	v_add_f32_e32 v11, v20, v8
	v_mul_f32_e32 v4, v4, v4
	v_fmac_f32_e32 v4, v5, v5
	v_fmac_f32_e32 v4, v6, v6
	v_fmac_f32_e32 v4, v7, v7
	v_add_f32_e32 v11, v11, v4
	v_pk_fma_f32 v[4:5], v[2:3], 0.5, v[34:35] op_sel_hi:[1,0,1]
	v_pk_fma_f32 v[2:3], v[0:1], 0.5, v[32:33] op_sel_hi:[1,0,1]
	v_or_b32_e32 v8, 0x100, v16
	v_mul_f32_e32 v0, v2, v2
	v_fmac_f32_e32 v0, v3, v3
	v_fmac_f32_e32 v0, v4, v4
	v_fmac_f32_e32 v0, v5, v5
	v_add_f32_e32 v0, v11, v0
	ds_bpermute_b32 v1, v192, v0
	v_mov_b32_e32 v9, v17
	v_or_b32_e32 v16, 0x120, v16
	v_lshl_add_u64 v[8:9], s[4:5], 0, v[8:9]
	v_cvt_pk_bf16_f32 v11, v6, v7
	s_waitcnt lgkmcnt(0)
	v_add_f32_e32 v0, v0, v1
	ds_bpermute_b32 v1, v116, v0
	v_lshl_add_u64 v[6:7], s[4:5], 0, v[16:17]
	s_nop 1
	v_mov_b32_e32 v240, v10
	v_mov_b32_e32 v241, v11
	v_lshl_add_u64 v[244:245], v[8:9], 0, v[246:247]
	global_store_dwordx4 v[18:19], v[2:5], off offset:576
	s_nop 1
	v_cvt_pk_bf16_f32 v2, v2, v3
	v_cvt_pk_bf16_f32 v3, v4, v5
	v_mov_b32_e32 v242, v2
	v_mov_b32_e32 v243, v3
	s_nop 1
	v_permlane16_swap_b32 v240, v242
	v_permlane16_swap_b32 v241, v243
	global_store_dwordx4 v[244:245], v[240:243], off
	s_and_saveexec_b64 s[28:29], s[6:7]
	s_cbranch_execz .LBB0_1800
	v_lshlrev_b64 v[2:3], 6, v[48:49]
	v_lshl_add_u64 v[2:3], s[14:15], 0, v[2:3]
	v_lshl_add_u64 v[2:3], s[26:27], 2, v[2:3]
	s_lshl_b32 s18, s53, 2
	v_lshl_add_u64 v[2:3], v[2:3], 0, s[18:19]
	s_waitcnt lgkmcnt(0)
	v_add_f32_e32 v0, v0, v1
	v_mov_b32_e32 v236, v2
	v_mov_b32_e32 v237, v3
	v_mov_b32_e32 v238, v0
	s_or_b64 exec, exec, s[28:29]
	s_nop 4
	v_permlane16_swap_b32 v236, v232
	v_permlane16_swap_b32 v237, v233
	v_permlane16_swap_b32 v238, v234
	s_mov_b64 s[28:29], exec
	s_mov_b64 exec, 0xffffffff
	global_store_dword v[236:237], v238, off
	s_mov_b64 exec, s[28:29]
	s_branch .LBB0_1800

.LBB0_2177:
	s_or_b64 exec, exec, s[30:31]
	s_nop 4
	v_permlane16_swap_b32 v236, v232
	v_permlane16_swap_b32 v237, v233
	v_permlane16_swap_b32 v238, v234
	s_mov_b64 s[30:31], exec
	s_mov_b64 exec, 0xffffffff
	global_store_dword v[236:237], v238, off
	s_mov_b64 exec, s[30:31]
	v_lshl_add_u64 v[50:51], v[164:165], 0, s[16:17]
	s_waitcnt lgkmcnt(0)
	v_lshlrev_b64 v[32:33], 12, v[50:51]
	v_lshl_add_u64 v[32:33], v[166:167], 0, v[32:33]
	global_load_dwordx4 v[52:55], v[32:33], off
	global_load_dwordx4 v[56:59], v[32:33], off offset:64
	global_load_dwordx4 v[60:63], v[32:33], off offset:512
	global_load_dwordx4 v[64:67], v[32:33], off offset:576
	v_lshl_add_u64 v[48:49], v[164:165], 0, s[18:19]
	v_lshlrev_b64 v[32:33], 12, v[48:49]
	v_lshl_add_u64 v[32:33], v[166:167], 0, v[32:33]
	global_load_dwordx4 v[44:47], v[32:33], off
	global_load_dwordx4 v[40:43], v[32:33], off offset:64
	global_load_dwordx4 v[36:39], v[32:33], off offset:512
	s_nop 0
	global_load_dwordx4 v[32:35], v[32:33], off offset:576
	v_lshlrev_b64 v[68:69], 10, v[50:51]
	v_lshl_add_u64 v[68:69], v[68:69], 0, v[162:163]
	v_lshl_add_u64 v[70:71], v[68:69], 2, s[78:79]
	v_lshlrev_b64 v[68:69], 1, v[68:69]
	v_lshl_add_u64 v[72:73], s[2:3], 0, v[68:69]
	s_waitcnt vmcnt(0)
	v_or_b32_e32 v74, 32, v68
	v_mov_b32_e32 v75, v69
	v_or_b32_e32 v76, 0x100, v68
	v_mov_b32_e32 v77, v69
	v_or_b32_e32 v68, 0x120, v68
	v_lshl_add_u64 v[74:75], s[2:3], 0, v[74:75]
	v_lshl_add_u64 v[76:77], s[2:3], 0, v[76:77]
	s_waitcnt vmcnt(0)
	v_pk_add_f32 v[28:29], v[28:29], v[52:53]
	v_pk_add_f32 v[24:25], v[24:25], v[56:57]
	v_pk_add_f32 v[20:21], v[20:21], v[60:61]
	v_mul_f32_e32 v56, v28, v28
	v_mul_f32_e32 v57, v24, v24
	v_pk_add_f32 v[30:31], v[30:31], v[54:55]
	v_pk_add_f32 v[26:27], v[26:27], v[58:59]
	v_pk_add_f32 v[52:53], v[16:17], v[64:65]
	v_mul_f32_e32 v58, v20, v20
	v_fmac_f32_e32 v56, v29, v29
	v_fmac_f32_e32 v57, v25, v25
	v_pk_add_f32 v[22:23], v[22:23], v[62:63]
	v_mul_f32_e32 v59, v52, v52
	v_fmac_f32_e32 v58, v21, v21
	v_fmac_f32_e32 v56, v30, v30
	v_fmac_f32_e32 v57, v26, v26
	v_pk_add_f32 v[54:55], v[18:19], v[66:67]
	v_cvt_pk_bf16_f32 v16, v28, v29
	v_fmac_f32_e32 v59, v53, v53
	v_fmac_f32_e32 v58, v22, v22
	v_fmac_f32_e32 v56, v31, v31
	v_fmac_f32_e32 v57, v27, v27
	global_store_dwordx4 v[70:71], v[28:31], off
	v_cvt_pk_bf16_f32 v17, v30, v31
	s_nop 1
	v_mov_b32_e32 v240, v16
	v_mov_b32_e32 v241, v17
	v_lshl_add_u64 v[244:245], v[72:73], 0, v[246:247]
	v_fmac_f32_e32 v59, v54, v54
	v_fmac_f32_e32 v58, v23, v23
	v_add_f32_e32 v16, v56, v57
	v_add_f32_e32 v16, v16, v58
	v_fmac_f32_e32 v59, v55, v55
	v_add_f32_e32 v16, v16, v59
	ds_bpermute_b32 v17, v188, v16
	v_cvt_pk_bf16_f32 v18, v24, v25
	v_cvt_pk_bf16_f32 v19, v26, v27
	v_cvt_pk_bf16_f32 v28, v20, v21
	global_store_dwordx4 v[70:71], v[24:27], off offset:64
	v_mov_b32_e32 v242, v18
	v_mov_b32_e32 v243, v19
	s_nop 1
	v_permlane16_swap_b32 v240, v242
	v_permlane16_swap_b32 v241, v243
	global_store_dwordx4 v[244:245], v[240:243], off
	s_waitcnt lgkmcnt(0)
	v_add_f32_e32 v16, v16, v17
	ds_bpermute_b32 v17, v116, v16
	v_cvt_pk_bf16_f32 v29, v22, v23
	v_lshl_add_u64 v[18:19], s[2:3], 0, v[68:69]
	global_store_dwordx4 v[70:71], v[20:23], off offset:512
	s_nop 1
	v_mov_b32_e32 v240, v28
	v_mov_b32_e32 v241, v29
	v_lshl_add_u64 v[244:245], v[76:77], 0, v[246:247]
	global_store_dwordx4 v[70:71], v[52:55], off offset:576
	v_cvt_pk_bf16_f32 v20, v52, v53
	v_cvt_pk_bf16_f32 v21, v54, v55
	v_mov_b32_e32 v242, v20
	v_mov_b32_e32 v243, v21
	s_nop 1
	v_permlane16_swap_b32 v240, v242
	v_permlane16_swap_b32 v241, v243
	global_store_dwordx4 v[244:245], v[240:243], off
	s_and_saveexec_b64 s[30:31], s[6:7]
	s_cbranch_execz .LBB0_2179
	v_lshlrev_b64 v[18:19], 6, v[50:51]
	v_lshl_add_u64 v[18:19], s[4:5], 0, v[18:19]
	v_lshl_add_u64 v[18:19], s[28:29], 2, v[18:19]
	s_lshl_b32 s12, s53, 2
	v_lshl_add_u64 v[18:19], v[18:19], 0, s[12:13]
	s_waitcnt lgkmcnt(0)
	v_add_f32_e32 v16, v16, v17
	v_mov_b32_e32 v232, v18
	v_mov_b32_e32 v233, v19
	v_mov_b32_e32 v234, v16
.LBB0_2179:
	s_or_b64 exec, exec, s[30:31]
	s_waitcnt lgkmcnt(0)
	v_lshlrev_b64 v[16:17], 10, v[48:49]
	v_lshl_add_u64 v[16:17], v[16:17], 0, v[162:163]
	v_lshl_add_u64 v[18:19], v[16:17], 2, s[78:79]
	v_lshlrev_b64 v[16:17], 1, v[16:17]
	v_pk_add_f32 v[14:15], v[14:15], v[46:47]
	v_pk_add_f32 v[12:13], v[12:13], v[44:45]
	v_lshl_add_u64 v[20:21], s[2:3], 0, v[16:17]
	global_store_dwordx4 v[18:19], v[12:15], off
	v_cvt_pk_bf16_f32 v22, v12, v13
	v_cvt_pk_bf16_f32 v23, v14, v15
	s_nop 1
	v_mov_b32_e32 v240, v22
	v_mov_b32_e32 v241, v23
	v_lshl_add_u64 v[244:245], v[20:21], 0, v[246:247]
	v_mul_f32_e32 v20, v12, v12
	v_fmac_f32_e32 v20, v13, v13
	v_pk_add_f32 v[10:11], v[10:11], v[42:43]
	v_pk_add_f32 v[8:9], v[8:9], v[40:41]
	v_fmac_f32_e32 v20, v14, v14
	global_store_dwordx4 v[18:19], v[8:11], off offset:64
	v_or_b32_e32 v12, 32, v16
	v_mov_b32_e32 v13, v17
	v_cvt_pk_bf16_f32 v14, v8, v9
	v_mul_f32_e32 v8, v8, v8
	v_lshl_add_u64 v[12:13], s[2:3], 0, v[12:13]
	v_fmac_f32_e32 v8, v9, v9
	v_pk_add_f32 v[6:7], v[6:7], v[38:39]
	v_pk_add_f32 v[4:5], v[4:5], v[36:37]
	v_fmac_f32_e32 v20, v15, v15
	v_cvt_pk_bf16_f32 v15, v10, v11
	v_mov_b32_e32 v242, v14
	v_mov_b32_e32 v243, v15
	s_nop 1
	v_permlane16_swap_b32 v240, v242
	v_permlane16_swap_b32 v241, v243
	global_store_dwordx4 v[244:245], v[240:243], off
	v_fmac_f32_e32 v8, v10, v10
	global_store_dwordx4 v[18:19], v[4:7], off offset:512
	v_cvt_pk_bf16_f32 v10, v4, v5
	v_fmac_f32_e32 v8, v11, v11
	v_add_f32_e32 v11, v20, v8
	v_mul_f32_e32 v4, v4, v4
	v_fmac_f32_e32 v4, v5, v5
	v_fmac_f32_e32 v4, v6, v6
	v_fmac_f32_e32 v4, v7, v7
	v_add_f32_e32 v11, v11, v4
	v_pk_add_f32 v[4:5], v[2:3], v[34:35]
	v_pk_add_f32 v[2:3], v[0:1], v[32:33]
	v_or_b32_e32 v8, 0x100, v16
	v_mul_f32_e32 v0, v2, v2
	v_fmac_f32_e32 v0, v3, v3
	v_fmac_f32_e32 v0, v4, v4
	v_fmac_f32_e32 v0, v5, v5
	v_add_f32_e32 v0, v11, v0
	ds_bpermute_b32 v1, v188, v0
	v_mov_b32_e32 v9, v17
	v_or_b32_e32 v16, 0x120, v16
	v_lshl_add_u64 v[8:9], s[2:3], 0, v[8:9]
	v_cvt_pk_bf16_f32 v11, v6, v7
	s_waitcnt lgkmcnt(0)
	v_add_f32_e32 v0, v0, v1
	ds_bpermute_b32 v1, v116, v0
	v_lshl_add_u64 v[6:7], s[2:3], 0, v[16:17]
	s_nop 1
	v_mov_b32_e32 v240, v10
	v_mov_b32_e32 v241, v11
	v_lshl_add_u64 v[244:245], v[8:9], 0, v[246:247]
	global_store_dwordx4 v[18:19], v[2:5], off offset:576
	s_nop 1
	v_cvt_pk_bf16_f32 v2, v2, v3
	v_cvt_pk_bf16_f32 v3, v4, v5
	v_mov_b32_e32 v242, v2
	v_mov_b32_e32 v243, v3
	s_nop 1
	v_permlane16_swap_b32 v240, v242
	v_permlane16_swap_b32 v241, v243
	global_store_dwordx4 v[244:245], v[240:243], off
	s_and_saveexec_b64 s[30:31], s[6:7]
	s_cbranch_execz .LBB0_2156
	v_lshlrev_b64 v[2:3], 6, v[48:49]
	v_lshl_add_u64 v[2:3], s[4:5], 0, v[2:3]
	v_lshl_add_u64 v[2:3], s[28:29], 2, v[2:3]
	s_lshl_b32 s12, s53, 2
	v_lshl_add_u64 v[2:3], v[2:3], 0, s[12:13]
	s_waitcnt lgkmcnt(0)
	v_add_f32_e32 v0, v0, v1
	v_mov_b32_e32 v236, v2
	v_mov_b32_e32 v237, v3
	v_mov_b32_e32 v238, v0
	s_or_b64 exec, exec, s[30:31]
	s_nop 4
	v_permlane16_swap_b32 v236, v232
	v_permlane16_swap_b32 v237, v233
	v_permlane16_swap_b32 v238, v234
	s_mov_b64 s[30:31], exec
	s_mov_b64 exec, 0xffffffff
	global_store_dword v[236:237], v238, off
	s_mov_b64 exec, s[30:31]
	s_branch .LBB0_2156
